# speedup vs baseline: 1.0048x; 1.0048x over previous
.LBB0_99:
	v_ashrrev_i32_e32 v37, 31, v36
	v_add_u32_e32 v30, s98, v36
	v_ashrrev_i32_e32 v31, 31, v30
	v_lshl_add_u64 v[96:97], v[36:37], 4, s[10:11]
	v_lshlrev_b64 v[56:57], 11, v[36:37]
	v_lshl_add_u64 v[56:57], v[22:23], 0, v[56:57]
	v_lshl_add_u64 v[98:99], v[30:31], 4, s[10:11]
	v_lshlrev_b64 v[58:59], 11, v[30:31]
	v_lshl_add_u64 v[58:59], v[22:23], 0, v[58:59]
	global_load_dwordx4 v[18:21], v[96:97], off
	global_load_dwordx2 v[46:47], v[56:57], off
	global_load_dwordx2 v[44:45], v[56:57], off offset:512
	global_load_dwordx2 v[40:41], v[56:57], off offset:1024
	global_load_dwordx2 v[38:39], v[56:57], off offset:1536
	global_load_dwordx4 v[52:55], v[98:99], off
	global_load_dwordx2 v[26:27], v[58:59], off
	global_load_dwordx2 v[28:29], v[58:59], off offset:512
	global_load_dwordx2 v[32:33], v[58:59], off offset:1024
	global_load_dwordx2 v[34:35], v[58:59], off offset:1536
	s_waitcnt vmcnt(0)
.Lfin_top:
	v_add_f32_e32 v1, v52, v53
	v_add_f32_e32 v1, v54, v1
	v_add_f32_e32 v1, v55, v1
	v_fmamk_f32 v1, v1, 0x3a800000, v208
	v_cmp_gt_f32_e64 s[4:5], s95, v1
	v_mul_f32_e32 v50, 0x4b800000, v1
	s_nop 0
	v_cndmask_b32_e64 v1, v1, v50, s[4:5]
	v_rsq_f32_e32 v1, v1
	s_nop 0
	v_mul_f32_e32 v50, 0x45800000, v1
	v_cndmask_b32_e64 v42, v1, v50, s[4:5]
	v_add_f32_e32 v1, v18, v19
	v_add_f32_e32 v1, v20, v1
	v_add_f32_e32 v1, v21, v1
	v_fmamk_f32 v1, v1, 0x3a800000, v208
	v_cmp_gt_f32_e64 s[4:5], s95, v1
	v_mul_f32_e32 v50, 0x4b800000, v1
	s_nop 0
	v_cndmask_b32_e64 v1, v1, v50, s[4:5]
	v_rsq_f32_e32 v1, v1
	s_nop 0
	v_mul_f32_e32 v50, 0x45800000, v1
	v_cndmask_b32_e64 v48, v1, v50, s[4:5]
	v_lshlrev_b32_e32 v60, 16, v46
	v_and_b32_e32 v61, 0xffff0000, v46
	v_lshlrev_b32_e32 v62, 16, v47
	v_and_b32_e32 v63, 0xffff0000, v47
	v_pk_mul_f32 v[60:61], v[48:49], v[60:61] op_sel_hi:[0,1]
	v_pk_mul_f32 v[62:63], v[48:49], v[62:63] op_sel_hi:[0,1]
	v_pk_mul_f32 v[60:61], v[14:15], v[60:61]
	v_pk_mul_f32 v[62:63], v[16:17], v[62:63]
	v_lshlrev_b32_e32 v64, 16, v44
	v_and_b32_e32 v65, 0xffff0000, v44
	v_lshlrev_b32_e32 v66, 16, v45
	v_and_b32_e32 v67, 0xffff0000, v45
	v_pk_mul_f32 v[64:65], v[48:49], v[64:65] op_sel_hi:[0,1]
	v_pk_mul_f32 v[66:67], v[48:49], v[66:67] op_sel_hi:[0,1]
	v_pk_mul_f32 v[64:65], v[10:11], v[64:65]
	v_pk_mul_f32 v[66:67], v[12:13], v[66:67]
	v_lshlrev_b32_e32 v68, 16, v40
	v_and_b32_e32 v69, 0xffff0000, v40
	v_lshlrev_b32_e32 v70, 16, v41
	v_and_b32_e32 v71, 0xffff0000, v41
	v_pk_mul_f32 v[68:69], v[48:49], v[68:69] op_sel_hi:[0,1]
	v_pk_mul_f32 v[70:71], v[48:49], v[70:71] op_sel_hi:[0,1]
	v_pk_mul_f32 v[68:69], v[6:7], v[68:69]
	v_pk_mul_f32 v[70:71], v[8:9], v[70:71]
	v_lshlrev_b32_e32 v72, 16, v38
	v_and_b32_e32 v73, 0xffff0000, v38
	v_lshlrev_b32_e32 v74, 16, v39
	v_and_b32_e32 v75, 0xffff0000, v39
	v_pk_mul_f32 v[72:73], v[48:49], v[72:73] op_sel_hi:[0,1]
	v_pk_mul_f32 v[74:75], v[48:49], v[74:75] op_sel_hi:[0,1]
	v_pk_mul_f32 v[72:73], v[2:3], v[72:73]
	v_pk_mul_f32 v[74:75], v[4:5], v[74:75]
	v_lshlrev_b32_e32 v76, 16, v26
	v_and_b32_e32 v77, 0xffff0000, v26
	v_lshlrev_b32_e32 v78, 16, v27
	v_and_b32_e32 v79, 0xffff0000, v27
	v_pk_mul_f32 v[76:77], v[42:43], v[76:77] op_sel_hi:[0,1]
	v_pk_mul_f32 v[78:79], v[42:43], v[78:79] op_sel_hi:[0,1]
	v_pk_mul_f32 v[76:77], v[14:15], v[76:77]
	v_pk_mul_f32 v[78:79], v[16:17], v[78:79]
	v_lshlrev_b32_e32 v80, 16, v28
	v_and_b32_e32 v81, 0xffff0000, v28
	v_lshlrev_b32_e32 v82, 16, v29
	v_and_b32_e32 v83, 0xffff0000, v29
	v_pk_mul_f32 v[80:81], v[42:43], v[80:81] op_sel_hi:[0,1]
	v_pk_mul_f32 v[82:83], v[42:43], v[82:83] op_sel_hi:[0,1]
	v_pk_mul_f32 v[80:81], v[10:11], v[80:81]
	v_pk_mul_f32 v[82:83], v[12:13], v[82:83]
	v_lshlrev_b32_e32 v84, 16, v32
	v_and_b32_e32 v85, 0xffff0000, v32
	v_lshlrev_b32_e32 v86, 16, v33
	v_and_b32_e32 v87, 0xffff0000, v33
	v_pk_mul_f32 v[84:85], v[42:43], v[84:85] op_sel_hi:[0,1]
	v_pk_mul_f32 v[86:87], v[42:43], v[86:87] op_sel_hi:[0,1]
	v_pk_mul_f32 v[84:85], v[6:7], v[84:85]
	v_pk_mul_f32 v[86:87], v[8:9], v[86:87]
	v_lshlrev_b32_e32 v88, 16, v34
	v_and_b32_e32 v89, 0xffff0000, v34
	v_lshlrev_b32_e32 v90, 16, v35
	v_and_b32_e32 v91, 0xffff0000, v35
	v_pk_mul_f32 v[88:89], v[42:43], v[88:89] op_sel_hi:[0,1]
	v_pk_mul_f32 v[90:91], v[42:43], v[90:91] op_sel_hi:[0,1]
	v_pk_mul_f32 v[88:89], v[2:3], v[88:89]
	v_pk_mul_f32 v[90:91], v[4:5], v[90:91]
	v_lshlrev_b64 v[92:93], 12, v[36:37]
	v_lshl_add_u64 v[92:93], v[24:25], 0, v[92:93]
	v_lshlrev_b64 v[94:95], 12, v[30:31]
	v_lshl_add_u64 v[94:95], v[24:25], 0, v[94:95]
	v_cmp_gt_i32_e32 vcc, s91, v30
	s_mov_b64 s[12:13], vcc
	v_add_u32_e32 v36, s98, v30
	v_cmp_lt_i32_e32 vcc, s93, v36
	s_cbranch_vccnz .Lfin_last
	v_ashrrev_i32_e32 v37, 31, v36
	v_add_u32_e32 v30, s98, v36
	v_ashrrev_i32_e32 v31, 31, v30
	v_lshl_add_u64 v[96:97], v[36:37], 4, s[10:11]
	v_lshlrev_b64 v[56:57], 11, v[36:37]
	v_lshl_add_u64 v[56:57], v[22:23], 0, v[56:57]
	v_lshl_add_u64 v[98:99], v[30:31], 4, s[10:11]
	v_lshlrev_b64 v[58:59], 11, v[30:31]
	v_lshl_add_u64 v[58:59], v[22:23], 0, v[58:59]
	global_load_dwordx4 v[18:21], v[96:97], off
	global_load_dwordx2 v[46:47], v[56:57], off
	global_load_dwordx2 v[44:45], v[56:57], off offset:512
	global_load_dwordx2 v[40:41], v[56:57], off offset:1024
	global_load_dwordx2 v[38:39], v[56:57], off offset:1536
	global_load_dwordx4 v[52:55], v[98:99], off
	global_load_dwordx2 v[26:27], v[58:59], off
	global_load_dwordx2 v[28:29], v[58:59], off offset:512
	global_load_dwordx2 v[32:33], v[58:59], off offset:1024
	global_load_dwordx2 v[34:35], v[58:59], off offset:1536
	global_store_dwordx4 v[92:93], v[60:63], off
	global_store_dwordx4 v[92:93], v[64:67], off offset:1024
	global_store_dwordx4 v[92:93], v[68:71], off offset:2048
	global_store_dwordx4 v[92:93], v[72:75], off offset:3072
	s_cmp_eq_u64 s[12:13], 0
	s_cbranch_scc1 .Lfin_noB0
	global_store_dwordx4 v[94:95], v[76:79], off
	global_store_dwordx4 v[94:95], v[80:83], off offset:1024
	global_store_dwordx4 v[94:95], v[84:87], off offset:2048
	global_store_dwordx4 v[94:95], v[88:91], off offset:3072
.Lfin_noB0:
	s_waitcnt vmcnt(8)
	s_branch .Lfin_top
.Lfin_last:
	global_store_dwordx4 v[92:93], v[60:63], off
	global_store_dwordx4 v[92:93], v[64:67], off offset:1024
	global_store_dwordx4 v[92:93], v[68:71], off offset:2048
	global_store_dwordx4 v[92:93], v[72:75], off offset:3072
	s_cmp_eq_u64 s[12:13], 0
	s_cbranch_scc1 .Lfin_noB1
	global_store_dwordx4 v[94:95], v[76:79], off
	global_store_dwordx4 v[94:95], v[80:83], off offset:1024
	global_store_dwordx4 v[94:95], v[84:87], off offset:2048
	global_store_dwordx4 v[94:95], v[88:91], off offset:3072
.Lfin_noB1:
	s_branch .LBB0_151
.LBB0_103:
	s_or_b64 exec, exec, s[2:3]
	s_movk_i32 s0, 0x100
